# final rmsnorm split: rows of tiles without leftover units are normalised by the idle workgroups during the second tail phase (barrier 13|21 restored); the last phase handles only leftover-tile rows
# speedup vs baseline: 1.0005x; 1.0005x over previous
; DI void final_norm_rows(const Prm& p, int gw, int ngw, int lane) {
;     for (int r = gw; r < ROW_META; r += ngw) {
;         float* x = p.out + (size_t)r * D; f32x4 v[4]; float ss = 0.f;
; #pragma unroll
;         for (int j = 0; j < 4; ++j) { v[j] = ((const f32x4*)x)[lane + 64 * j]; ss += v[j].x * v[j].x + v[j].y * v[j].y + v[j].z * v[j].z + v[j].w * v[j].w; }
;         ss = wave_sum(ss); const float rstd = rsqrtf(ss * (1.f / D) + 1e-6f);
.Len_start:
	s_mov_b64 s[12:13], vcc
	v_readfirstlane_b32 s0, v212
	s_lshr_b32 s0, s0, 6
	s_sub_i32 s2, s3, 72
	s_lshl_b32 s2, s2, 3
	s_add_i32 s0, s0, s2
	v_and_b32_e32 v160, 63, v212
	v_lshlrev_b32_e32 v160, 4, v160
	v_mov_b32_e32 v161, 0
	v_lshl_add_u64 v[162:163], s[28:29], 0, v[160:161]
	v_add_u32_e32 v160, 0xc00, v160
	v_mov_b32_e32 v4, 0x358637bd
	s_mov_b32 s24, 0x800000
	global_load_dwordx4 v[116:119], v[162:163], off
	global_load_dwordx4 v[120:123], v[162:163], off offset:1024
	global_load_dwordx4 v[124:127], v[162:163], off offset:2048
	global_load_dwordx4 v[128:131], v[162:163], off offset:3072
	s_sub_i32 s0, s0, 1472
.Len_nx0:
	s_add_i32 s0, s0, 1472
	s_cmp_lt_i32 s0, 0x8800
	s_cbranch_scc0 .Len_none0
	s_lshr_b32 s25, s0, 8
	s_lshr_b32 s26, s25, 5
	s_mov_b32 s27, 0x1f0000
	s_cmp_eq_u32 s26, 1
	s_cselect_b32 s27, 0x7c00e3, s27
	s_cmp_eq_u32 s26, 2
	s_cselect_b32 s27, 0xf0008f, s27
	s_cmp_eq_u32 s26, 3
	s_cselect_b32 s27, 0xf0000f, s27
	s_cmp_eq_u32 s26, 4
	s_cselect_b32 s27, 0, s27
	s_and_b32 s25, s25, 31
	s_lshr_b32 s27, s27, s25
	s_and_b32 s27, s27, 1
	s_cmp_eq_u32 s27, 1
	s_cbranch_scc1 .Len_nx0
	s_mov_b32 s2, 1
	s_branch .Len_got0
.Len_none0:
	s_mov_b32 s2, 0
.Len_got0:
	s_cmp_eq_u32 s2, 0
	s_cbranch_scc1 .Len_drain
	s_lshl_b32 s10, s0, 12
	s_add_u32 s10, s30, s10
	s_addc_u32 s11, s31, 0
	v_lshl_add_u64 v[156:157], s[10:11], 0, v[160:161]
	global_load_dwordx4 v[140:143], v[156:157], off offset:-3072
	global_load_dwordx4 v[144:147], v[156:157], off offset:-2048
	global_load_dwordx4 v[148:151], v[156:157], off offset:-1024
	global_load_dwordx4 v[152:155], v[156:157], off
	s_waitcnt vmcnt(0)
.Len_loop:
	s_waitcnt vmcnt(4)
	v_mov_b64_e32 v[100:101], v[140:141]
	v_mov_b64_e32 v[102:103], v[142:143]
	v_mov_b64_e32 v[104:105], v[144:145]
	v_mov_b64_e32 v[106:107], v[146:147]
	v_mov_b64_e32 v[108:109], v[148:149]
	v_mov_b64_e32 v[110:111], v[150:151]
	v_mov_b64_e32 v[112:113], v[152:153]
	v_mov_b64_e32 v[114:115], v[154:155]
	v_mov_b64_e32 v[158:159], v[156:157]

; DI void final_norm_rows(const Prm& p, int gw, int ngw, int lane) {
;     ...
;         float* x = p.out + (size_t)r * D; f32x4 v[4]; float ss = 0.f;
; #pragma unroll
;         for (int j = 0; j < 4; ++j) { v[j] = ((const f32x4*)x)[lane + 64 * j]; ss += v[j].x * v[j].x + v[j].y * v[j].y + v[j].z * v[j].z + v[j].w * v[j].w; }
;         ss = wave_sum(ss); const float rstd = rsqrtf(ss * (1.f / D) + 1e-6f);
; #pragma unroll
;         for (int j = 0; j < 4; ++j) { const f32x4 g = ((const f32x4*)p.final_norm)[lane + 64 * j]; ((f32x4*)x)[lane + 64 * j] = (f32x4){v[j].x * rstd * g.x, v[j].y * rstd * g.y, v[j].z * rstd * g.z, v[j].w * rstd * g.w}; }
;     }
.Len_got1:
	s_cmp_eq_u32 s2, 0
	s_cbranch_scc1 .Len_nopf
	s_lshl_b32 s10, s0, 12
	s_add_u32 s10, s30, s10
	s_addc_u32 s11, s31, 0
	v_lshl_add_u64 v[156:157], s[10:11], 0, v[160:161]
	global_load_dwordx4 v[140:143], v[156:157], off offset:-3072
	global_load_dwordx4 v[144:147], v[156:157], off offset:-2048
	global_load_dwordx4 v[148:151], v[156:157], off offset:-1024
	global_load_dwordx4 v[152:155], v[156:157], off
.Len_nopf:
	v_mov_b32_e32 v28, v101
	v_mov_b32_e32 v29, v105
	v_mov_b32_e32 v26, v100
	v_mov_b32_e32 v27, v104
	v_mov_b32_e32 v36, v109
	v_mov_b32_e32 v37, v113
	v_pk_mul_f32 v[28:29], v[28:29], v[28:29]
	v_mov_b32_e32 v30, v102
	v_mov_b32_e32 v31, v106
	v_mov_b32_e32 v34, v108
	v_mov_b32_e32 v35, v112
	v_pk_mul_f32 v[36:37], v[36:37], v[36:37]
	v_pk_fma_f32 v[26:27], v[26:27], v[26:27], v[28:29]
	v_mov_b32_e32 v32, v103
	v_mov_b32_e32 v33, v107
	v_mov_b32_e32 v38, v110
	v_mov_b32_e32 v39, v114
	v_pk_fma_f32 v[28:29], v[34:35], v[34:35], v[36:37]
	v_pk_fma_f32 v[26:27], v[30:31], v[30:31], v[26:27]
	v_mov_b32_e32 v40, v111
	v_mov_b32_e32 v41, v115
	v_pk_fma_f32 v[28:29], v[38:39], v[38:39], v[28:29]
	v_pk_fma_f32 v[26:27], v[32:33], v[32:33], v[26:27]
	v_pk_fma_f32 v[28:29], v[40:41], v[40:41], v[28:29]
	v_add_f32_e32 v5, v26, v27
	v_add_f32_e32 v5, v5, v28
	v_add_f32_e32 v5, v5, v29
	s_nop 1
	v_add_f32_dpp v5, v5, v5 quad_perm:[1,0,3,2] row_mask:0xf bank_mask:0xf bound_ctrl:1
	s_nop 1
	v_add_f32_dpp v5, v5, v5 quad_perm:[2,3,0,1] row_mask:0xf bank_mask:0xf bound_ctrl:1
	s_nop 1
	v_add_f32_dpp v5, v5, v5 row_half_mirror row_mask:0xf bank_mask:0xf bound_ctrl:1
	s_nop 1
	v_add_f32_dpp v5, v5, v5 row_mirror row_mask:0xf bank_mask:0xf bound_ctrl:1
	s_nop 0
	v_readlane_b32 s22, v5, 16
	v_readlane_b32 s23, v5, 48
	v_readlane_b32 s20, v5, 0
	v_readlane_b32 s21, v5, 32
	v_mov_b32_e32 v26, s22
	v_mov_b32_e32 v27, s23
	v_pk_add_f32 v[26:27], s[20:21], v[26:27]
	s_nop 0
	v_add_f32_e32 v5, v26, v27
	v_fmamk_f32 v5, v5, 0x3a800000, v4
	v_mul_f32_e32 v26, 0x4b800000, v5
	v_cmp_gt_f32_e32 vcc, s24, v5
	s_nop 1
	v_cndmask_b32_e32 v5, v5, v26, vcc
	v_rsq_f32_e32 v5, v5
	s_nop 0
	v_mul_f32_e32 v26, 0x45800000, v5
	v_cndmask_b32_e32 v26, v5, v26, vcc
	v_pk_mul_f32 v[6:7], v[100:101], v[26:27] op_sel_hi:[1,0]
	v_pk_mul_f32 v[8:9], v[102:103], v[26:27] op_sel_hi:[1,0]
	v_pk_mul_f32 v[6:7], v[116:117], v[6:7]
	v_pk_mul_f32 v[8:9], v[118:119], v[8:9]
	global_store_dwordx4 v[158:159], v[6:9], off offset:-3072
	s_nop 0
	v_pk_mul_f32 v[12:13], v[106:107], v[26:27] op_sel_hi:[1,0]
	v_pk_mul_f32 v[10:11], v[104:105], v[26:27] op_sel_hi:[1,0]
	v_pk_mul_f32 v[8:9], v[122:123], v[12:13]
	v_pk_mul_f32 v[6:7], v[120:121], v[10:11]
	global_store_dwordx4 v[158:159], v[6:9], off offset:-2048
	s_nop 0
	v_pk_mul_f32 v[10:11], v[110:111], v[26:27] op_sel_hi:[1,0]
	v_pk_mul_f32 v[12:13], v[108:109], v[26:27] op_sel_hi:[1,0]
	v_pk_mul_f32 v[8:9], v[126:127], v[10:11]
	v_pk_mul_f32 v[6:7], v[124:125], v[12:13]
	global_store_dwordx4 v[158:159], v[6:9], off offset:-1024
	s_nop 0
	v_pk_mul_f32 v[10:11], v[114:115], v[26:27] op_sel_hi:[1,0]
	v_pk_mul_f32 v[12:13], v[112:113], v[26:27] op_sel_hi:[1,0]
	v_pk_mul_f32 v[8:9], v[130:131], v[10:11]
	v_pk_mul_f32 v[6:7], v[128:129], v[12:13]
	global_store_dwordx4 v[158:159], v[6:9], off
	s_cmp_eq_u32 s2, 1
	s_cbranch_scc1 .Len_loop
.Len_drain:
	s_nop 0
	s_mov_b64 vcc, s[12:13]
	s_branch .LBB0_2514

; DI void final_norm_rows(const Prm& p, int gw, int ngw, int lane) {
;     for (int r = gw; r < ROW_META; r += ngw) {
;         float* x = p.out + (size_t)r * D; f32x4 v[4]; float ss = 0.f;
.LBB0_2630:
	s_or_b64 exec, exec, s[0:1]
	s_waitcnt lgkmcnt(0)
	s_barrier
	v_readlane_b32 s1, v247, 43
	v_readfirstlane_b32 s0, v212
	s_ashr_i32 s0, s0, 6
	s_add_i32 s0, s0, s1
	v_and_b32_e32 v160, 63, v212
	v_lshlrev_b32_e32 v160, 4, v160
	v_mov_b32_e32 v161, 0
	v_lshl_add_u64 v[162:163], s[28:29], 0, v[160:161]
	v_add_u32_e32 v160, 0xc00, v160
	v_mov_b32_e32 v4, 0x358637bd
	s_mov_b32 s24, 0x800000
	global_load_dwordx4 v[116:119], v[162:163], off
	global_load_dwordx4 v[120:123], v[162:163], off offset:1024
	global_load_dwordx4 v[124:127], v[162:163], off offset:2048
	global_load_dwordx4 v[128:131], v[162:163], off offset:3072
	s_sub_i32 s0, s0, 2048
.Lln_nx0:
	s_add_i32 s0, s0, 2048
	s_cmp_lt_i32 s0, 0x8800
	s_cbranch_scc0 .Lln_none0
	s_lshr_b32 s25, s0, 8
	s_lshr_b32 s26, s25, 5
	s_mov_b32 s27, 0x1f0000
	s_cmp_eq_u32 s26, 1
	s_cselect_b32 s27, 0x7c00e3, s27
	s_cmp_eq_u32 s26, 2
	s_cselect_b32 s27, 0xf0008f, s27
	s_cmp_eq_u32 s26, 3
	s_cselect_b32 s27, 0xf0000f, s27
	s_cmp_eq_u32 s26, 4
	s_cselect_b32 s27, 0, s27
	s_and_b32 s25, s25, 31
	s_lshr_b32 s27, s27, s25
	s_and_b32 s27, s27, 1
	s_cmp_eq_u32 s27, 0
	s_cbranch_scc1 .Lln_nx0
	s_mov_b32 s2, 1
	s_branch .Lln_got0

; DI void final_norm_rows(const Prm& p, int gw, int ngw, int lane) {
;     for (int r = gw; r < ROW_META; r += ngw) {
.Lln_drain:
	s_nop 0
.LBB0_2633:
	s_endpgm
